# v24 + static s_setprio 1 for waves 4-7 at kernel entry
# speedup vs baseline: 1.0020x; 1.0020x over previous
_Z14fwd_megakernel6Params:
	s_mov_b32 s92, s2
	v_readfirstlane_b32 s3, v0
	s_and_b32 s3, s3, 0x3ff
	s_cmpk_ge_u32 s3, 0x100
	s_cbranch_scc0 .Lprio_done
	s_setprio 1
.Lprio_done:
	s_load_dword s2, s[0:1], 0x4c4
	s_load_dwordx2 s[14:15], s[0:1], 0x4c8
	s_add_u32 s4, s0, 0x4c8
	s_addc_u32 s5, s1, 0
	s_waitcnt lgkmcnt(0)
	s_cmp_eq_u32 s2, 0x7fffffff
	s_cbranch_scc1 .LBB0_2
	v_and_b32_e32 v155, 0x3ff, v0
	s_load_dword s33, s[0:1], 0x4d0
	s_cbranch_execz .LBB0_3
	s_branch .LBB0_14
